# nontemporal hint on the read-once o and gate loads of the head-norm pass, on top of the four-slot overlap with nt weight stores
# baseline (speedup 1.0000x reference)
; #define LAS __attribute__((address_space(3)))
; __device__ __forceinline__ unsigned pk2(float lo, float hi) { return pg8::cvt_pk_bf16(lo, hi); }
; __device__ __forceinline__ void rec_loop_task(const P& p, unsigned char* ws, int l, LAS unsigned char* lds, int tk) {
;     ...
;     { const int c4 = (tid & 15) * 4, r0 = tid >> 4;
;       const f32x4 gn4 = *(const f32x4*)((gla ? p.gln + l * GV : p.hgn + l * HV) + vs * 64 + c4);
;       const bf16_t* gate = (const bf16_t*)(ws + (gla ? WS_RG : WS_GHG)) + (size_t)(b * SEQ) * 1024 + head * V + vs * 64 + c4;
;       bf16_t* og = (bf16_t*)(ws + WS_OG) + (size_t)(b * SEQ) * D + (gla ? 1024 : 0) + head * V + vs * 64 + c4;
;       const float* orow = op + c4;
; #pragma nounroll
;       for (int rb = 0; rb < SEQ; rb += 256) {
;           f32x4 ov[8]; u32x2 gw[8];
; #pragma unroll
;           for (int i = 0; i < 8; ++i) { const int r = rb + i * 32 + r0; ov[i] = *(const f32x4*)(orow + (size_t)r * D); gw[i] = *(const u32x2*)(gate + (size_t)r * 1024); }
; #pragma unroll
;           for (int i = 0; i < 8; ++i) { const int r = rb + i * 32 + r0; const float rs = ((const LAS float*)(lds + R_ORS))[r];
;               const float g0 = __uint_as_float(gw[i].x << 16), g1 = __uint_as_float(gw[i].x & 0xffff0000u), g2 = __uint_as_float(gw[i].y << 16), g3 = __uint_as_float(gw[i].y & 0xffff0000u);
;               u32x2 wv; wv.x = pk2(ov[i][0] * rs * gn4[0] * g0, ov[i][1] * rs * gn4[1] * g1); wv.y = pk2(ov[i][2] * rs * gn4[2] * g2, ov[i][3] * rs * gn4[3] * g3);
;               *(u32x2*)(og + (size_t)r * D) = wv; } } }
.LBB0_1112:
	v_lshl_add_u64 v[6:7], s[12:13], 0, v[42:43]
	v_add_co_u32_e32 v8, vcc, 0x36914000, v6
	v_lshl_add_u64 v[44:45], s[12:13], 0, v[40:41]
	s_nop 0
	v_addc_co_u32_e32 v9, vcc, 0, v7, vcc
	global_load_dwordx4 v[34:37], v[8:9], off nt
	global_load_dwordx2 v[58:59], v[44:45], off nt
	v_add_co_u32_e32 v8, vcc, 0x36954000, v6
	s_mov_b32 s1, 0x10000
	s_nop 0
	v_addc_co_u32_e32 v9, vcc, 0, v7, vcc
	global_load_dwordx4 v[30:33], v[8:9], off nt
	v_add_co_u32_e32 v8, vcc, s1, v44
	ds_read2_b32 v[62:63], v60 offset1:32
	s_nop 0
	v_addc_co_u32_e32 v9, vcc, 0, v45, vcc
	global_load_dwordx2 v[56:57], v[8:9], off nt
	v_add_co_u32_e32 v8, vcc, 0x36994000, v6
	s_mov_b32 s1, 0x3ab14000
	s_nop 0
	v_addc_co_u32_e32 v9, vcc, 0, v7, vcc
	global_load_dwordx4 v[26:29], v[8:9], off nt
	v_add_co_u32_e32 v8, vcc, s83, v44
	s_mov_b64 s[6:7], 0x100000
	s_nop 0
	v_addc_co_u32_e32 v9, vcc, 0, v45, vcc
	global_load_dwordx2 v[54:55], v[8:9], off nt
	v_add_co_u32_e32 v8, vcc, 0x369d4000, v6
	s_addk_i32 s0, 0x100
	s_nop 0
	v_addc_co_u32_e32 v9, vcc, 0, v7, vcc
	global_load_dwordx4 v[22:25], v[8:9], off nt
	v_add_co_u32_e32 v8, vcc, 0x30000, v44
	v_lshl_add_u64 v[40:41], v[40:41], 0, s[64:65]
	s_nop 0
	v_addc_co_u32_e32 v9, vcc, 0, v45, vcc
	global_load_dwordx2 v[52:53], v[8:9], off nt
	v_add_co_u32_e32 v8, vcc, 0x36a14000, v6
	s_cmpk_lt_u32 s0, 0x700
	s_nop 0
	v_addc_co_u32_e32 v9, vcc, 0, v7, vcc
	global_load_dwordx4 v[18:21], v[8:9], off nt
	v_add_co_u32_e32 v8, vcc, 0x40000, v44
	s_waitcnt vmcnt(8) lgkmcnt(0)
	v_pk_mul_f32 v[34:35], v[34:35], v[62:63] op_sel_hi:[1,0]
	v_addc_co_u32_e32 v9, vcc, 0, v45, vcc
	global_load_dwordx2 v[50:51], v[8:9], off nt
	v_add_co_u32_e32 v8, vcc, 0x36a54000, v6
	v_pk_mul_f32 v[34:35], v[2:3], v[34:35]
	s_nop 0
	v_addc_co_u32_e32 v9, vcc, 0, v7, vcc
	global_load_dwordx4 v[14:17], v[8:9], off nt
	v_add_co_u32_e32 v8, vcc, 0x50000, v44
	v_pk_mul_f32 v[36:37], v[36:37], v[62:63] op_sel_hi:[1,0]
	s_nop 0
	v_addc_co_u32_e32 v9, vcc, 0, v45, vcc
	global_load_dwordx2 v[48:49], v[8:9], off nt
	v_add_co_u32_e32 v8, vcc, 0x36a94000, v6
	v_pk_mul_f32 v[36:37], v[4:5], v[36:37]
	s_nop 0
	v_addc_co_u32_e32 v9, vcc, 0, v7, vcc
	global_load_dwordx4 v[10:13], v[8:9], off nt
	v_add_co_u32_e32 v8, vcc, 0x60000, v44
	s_nop 1
	v_addc_co_u32_e32 v9, vcc, 0, v45, vcc
	global_load_dwordx2 v[46:47], v[8:9], off nt
	v_add_co_u32_e32 v6, vcc, 0x36ad4000, v6
	s_nop 1
	v_addc_co_u32_e32 v7, vcc, 0, v7, vcc
	global_load_dwordx4 v[6:9], v[6:7], off nt
	v_add_co_u32_e32 v44, vcc, 0x70000, v44
	s_waitcnt vmcnt(13)
	v_lshlrev_b32_e32 v64, 16, v58
	v_addc_co_u32_e32 v45, vcc, 0, v45, vcc
	global_load_dwordx2 v[44:45], v[44:45], off nt
	v_and_b32_e32 v65, 0xffff0000, v58
	v_pk_mul_f32 v[34:35], v[34:35], v[64:65]
	s_nop 0
	v_cvt_pk_bf16_f32 v58, v34, v35
	v_lshlrev_b32_e32 v34, 16, v59
	v_and_b32_e32 v35, 0xffff0000, v59
	v_pk_mul_f32 v[34:35], v[36:37], v[34:35]
	s_nop 0
	v_cvt_pk_bf16_f32 v59, v34, v35
	v_lshl_add_u64 v[34:35], s[12:13], 0, v[38:39]
	v_add_co_u32_e32 v36, vcc, s1, v34
	s_mov_b32 s1, 0x3ab34000
	s_nop 0
	v_addc_co_u32_e32 v37, vcc, 0, v35, vcc
	global_store_dwordx2 v[36:37], v[58:59], off
	s_waitcnt vmcnt(13)
	v_lshlrev_b32_e32 v36, 16, v56
	v_and_b32_e32 v37, 0xffff0000, v56
	v_mov_b32_e32 v56, v63
	v_pk_mul_f32 v[30:31], v[30:31], v[56:57] op_sel_hi:[1,0]
	v_pk_mul_f32 v[32:33], v[32:33], v[56:57] op_sel_hi:[1,0]
	v_pk_mul_f32 v[30:31], v[2:3], v[30:31]
	v_pk_mul_f32 v[32:33], v[4:5], v[32:33]
	v_pk_mul_f32 v[30:31], v[30:31], v[36:37]
	v_lshlrev_b32_e32 v36, 16, v57
	v_and_b32_e32 v37, 0xffff0000, v57
	v_pk_mul_f32 v[32:33], v[32:33], v[36:37]
	v_cvt_pk_bf16_f32 v30, v30, v31
	v_cvt_pk_bf16_f32 v31, v32, v33
	v_add_co_u32_e32 v32, vcc, s1, v34
	s_mov_b32 s1, 0x3ab54000
	s_nop 0
	v_addc_co_u32_e32 v33, vcc, 0, v35, vcc
	global_store_dwordx2 v[32:33], v[30:31], off
	ds_read2_b32 v[30:31], v60 offset0:64 offset1:96
	s_waitcnt vmcnt(12)
	v_lshlrev_b32_e32 v32, 16, v54
	v_and_b32_e32 v33, 0xffff0000, v54
	v_lshl_add_u64 v[38:39], v[38:39], 0, s[6:7]
	s_mov_b64 s[6:7], 0x200000
	s_waitcnt lgkmcnt(0)
; #define LAS __attribute__((address_space(3)))
; __device__ __forceinline__ unsigned pk2(float lo, float hi) { return pg8::cvt_pk_bf16(lo, hi); }
; __device__ __forceinline__ void rec_loop_task(const P& p, unsigned char* ws, int l, LAS unsigned char* lds, int tk) {
;     ...
;           for (int i = 0; i < 8; ++i) { const int r = rb + i * 32 + r0; const float rs = ((const LAS float*)(lds + R_ORS))[r];
;               const float g0 = __uint_as_float(gw[i].x << 16), g1 = __uint_as_float(gw[i].x & 0xffff0000u), g2 = __uint_as_float(gw[i].y << 16), g3 = __uint_as_float(gw[i].y & 0xffff0000u);
;               u32x2 wv; wv.x = pk2(ov[i][0] * rs * gn4[0] * g0, ov[i][1] * rs * gn4[1] * g1); wv.y = pk2(ov[i][2] * rs * gn4[2] * g2, ov[i][3] * rs * gn4[3] * g3);
;               *(u32x2*)(og + (size_t)r * D) = wv; } } }
;     __syncthreads();
; }
; __device__ __forceinline__ void phase_rec(const P& p, unsigned char* ws, int l, LAS unsigned char* lds, int wg, int nwg) {
;     ...
;     for (int rl = 0; rl < REP_LOOP; ++rl) for (int tk = lrank; tk < 128; tk += nloop) rec_loop_task(p, ws, l, lds, tk);
	v_pk_mul_f32 v[26:27], v[26:27], v[30:31] op_sel_hi:[1,0]
	v_pk_mul_f32 v[28:29], v[28:29], v[30:31] op_sel_hi:[1,0]
	v_pk_mul_f32 v[26:27], v[2:3], v[26:27]
	v_pk_mul_f32 v[28:29], v[4:5], v[28:29]
	v_pk_mul_f32 v[26:27], v[26:27], v[32:33]
	v_lshlrev_b32_e32 v32, 16, v55
	v_and_b32_e32 v33, 0xffff0000, v55
	v_pk_mul_f32 v[28:29], v[28:29], v[32:33]
	v_cvt_pk_bf16_f32 v26, v26, v27
	v_cvt_pk_bf16_f32 v27, v28, v29
	v_add_co_u32_e32 v28, vcc, s1, v34
	s_mov_b32 s1, 0x3ab74000
	s_nop 0
	v_addc_co_u32_e32 v29, vcc, 0, v35, vcc
	global_store_dwordx2 v[28:29], v[26:27], off
	v_mov_b32_e32 v28, v31
	s_waitcnt vmcnt(12)
	v_pk_mul_f32 v[22:23], v[22:23], v[28:29] op_sel_hi:[1,0]
	s_waitcnt vmcnt(11)
	v_lshlrev_b32_e32 v26, 16, v52
	v_and_b32_e32 v27, 0xffff0000, v52
	v_pk_mul_f32 v[22:23], v[2:3], v[22:23]
	v_pk_mul_f32 v[24:25], v[24:25], v[28:29] op_sel_hi:[1,0]
	v_pk_mul_f32 v[22:23], v[22:23], v[26:27]
	v_lshlrev_b32_e32 v26, 16, v53
	v_and_b32_e32 v27, 0xffff0000, v53
	v_pk_mul_f32 v[24:25], v[4:5], v[24:25]
	v_cvt_pk_bf16_f32 v22, v22, v23
	v_pk_mul_f32 v[24:25], v[24:25], v[26:27]
	v_lshl_add_u64 v[42:43], v[42:43], 0, s[6:7]
	v_cvt_pk_bf16_f32 v23, v24, v25
	v_add_co_u32_e32 v24, vcc, s1, v34
	s_mov_b32 s1, 0x3ab94000
	s_nop 0
	v_addc_co_u32_e32 v25, vcc, 0, v35, vcc
	global_store_dwordx2 v[24:25], v[22:23], off
	ds_read2_b32 v[22:23], v60 offset0:128 offset1:160
	s_waitcnt vmcnt(10)
	v_lshlrev_b32_e32 v24, 16, v50
	v_and_b32_e32 v25, 0xffff0000, v50
	s_waitcnt lgkmcnt(0)
	v_pk_mul_f32 v[18:19], v[18:19], v[22:23] op_sel_hi:[1,0]
	s_nop 0
	v_pk_mul_f32 v[18:19], v[2:3], v[18:19]
	v_pk_mul_f32 v[20:21], v[20:21], v[22:23] op_sel_hi:[1,0]
	v_pk_mul_f32 v[18:19], v[18:19], v[24:25]
	v_lshlrev_b32_e32 v24, 16, v51
	v_and_b32_e32 v25, 0xffff0000, v51
	v_pk_mul_f32 v[20:21], v[4:5], v[20:21]
	v_cvt_pk_bf16_f32 v18, v18, v19
	v_pk_mul_f32 v[20:21], v[20:21], v[24:25]
	s_nop 0
	v_cvt_pk_bf16_f32 v19, v20, v21
	v_add_co_u32_e32 v20, vcc, s1, v34
	s_mov_b32 s1, 0x3abb4000
	s_nop 0
	v_addc_co_u32_e32 v21, vcc, 0, v35, vcc
	global_store_dwordx2 v[20:21], v[18:19], off
	v_mov_b32_e32 v20, v23
	s_waitcnt vmcnt(10)
	v_pk_mul_f32 v[14:15], v[14:15], v[20:21] op_sel_hi:[1,0]
	s_waitcnt vmcnt(9)
	v_lshlrev_b32_e32 v18, 16, v48
	v_and_b32_e32 v19, 0xffff0000, v48
	v_pk_mul_f32 v[14:15], v[2:3], v[14:15]
	v_pk_mul_f32 v[16:17], v[16:17], v[20:21] op_sel_hi:[1,0]
	v_pk_mul_f32 v[14:15], v[14:15], v[18:19]
	v_lshlrev_b32_e32 v18, 16, v49
	v_and_b32_e32 v19, 0xffff0000, v49
	v_pk_mul_f32 v[16:17], v[4:5], v[16:17]
	v_cvt_pk_bf16_f32 v14, v14, v15
	v_pk_mul_f32 v[16:17], v[16:17], v[18:19]
	s_nop 0
	v_cvt_pk_bf16_f32 v15, v16, v17
	v_add_co_u32_e32 v16, vcc, s1, v34
	s_mov_b32 s1, 0x3abd4000
	s_nop 0
	v_addc_co_u32_e32 v17, vcc, 0, v35, vcc
	global_store_dwordx2 v[16:17], v[14:15], off
	ds_read2_b32 v[14:15], v60 offset0:192 offset1:224
	s_waitcnt vmcnt(8)
	v_lshlrev_b32_e32 v16, 16, v46
	v_and_b32_e32 v17, 0xffff0000, v46
	v_add_u32_e32 v60, 0x400, v60
	s_waitcnt lgkmcnt(0)
	v_pk_mul_f32 v[10:11], v[10:11], v[14:15] op_sel_hi:[1,0]
	s_nop 0
	v_pk_mul_f32 v[10:11], v[2:3], v[10:11]
	v_pk_mul_f32 v[12:13], v[12:13], v[14:15] op_sel_hi:[1,0]
	v_pk_mul_f32 v[10:11], v[10:11], v[16:17]
	v_lshlrev_b32_e32 v16, 16, v47
	v_and_b32_e32 v17, 0xffff0000, v47
	v_pk_mul_f32 v[12:13], v[4:5], v[12:13]
	v_cvt_pk_bf16_f32 v10, v10, v11
	v_pk_mul_f32 v[12:13], v[12:13], v[16:17]
	s_nop 0
	v_cvt_pk_bf16_f32 v11, v12, v13
	v_add_co_u32_e32 v12, vcc, s1, v34
	s_nop 1
	v_addc_co_u32_e32 v13, vcc, 0, v35, vcc
	global_store_dwordx2 v[12:13], v[10:11], off
	v_mov_b32_e32 v12, v15
	s_waitcnt vmcnt(8)
	v_pk_mul_f32 v[6:7], v[6:7], v[12:13] op_sel_hi:[1,0]
	s_waitcnt vmcnt(7)
	v_lshlrev_b32_e32 v10, 16, v44
	v_and_b32_e32 v11, 0xffff0000, v44
	v_pk_mul_f32 v[6:7], v[2:3], v[6:7]
	v_pk_mul_f32 v[8:9], v[8:9], v[12:13] op_sel_hi:[1,0]
	v_pk_mul_f32 v[6:7], v[6:7], v[10:11]
	v_lshlrev_b32_e32 v10, 16, v45
	v_and_b32_e32 v11, 0xffff0000, v45
	v_pk_mul_f32 v[8:9], v[4:5], v[8:9]
	v_cvt_pk_bf16_f32 v6, v6, v7
	v_pk_mul_f32 v[8:9], v[8:9], v[10:11]
	s_nop 0
	v_cvt_pk_bf16_f32 v7, v8, v9
	v_add_co_u32_e32 v8, vcc, 0x3abf4000, v34
	s_nop 1
	v_addc_co_u32_e32 v9, vcc, 0, v35, vcc
	global_store_dwordx2 v[8:9], v[6:7], off
	s_cbranch_scc1 .LBB0_1112
	s_add_i32 s45, s45, s57
	s_cmpk_gt_i32 s45, 0x7f
	s_barrier
	s_cbranch_scc0 .LBB0_1078
